# on top of v62: P12 compressed-branch outputs stored with v_permlane32_swap pairs + 8 global_store_dwordx4 per head instead of 16 global_store_dwordx2
# baseline (speedup 1.0000x reference)
.LBB0_3642:
	s_mul_i32 s0, s57, 3
	v_lshl_add_u64 v[66:67], s[0:1], 2, v[132:133]
	global_load_dword v66, v[66:67], off
	s_add_i32 s55, s55, 1
	s_lshl_b32 s0, s56, 1
	v_lshl_add_u64 v[68:69], v[134:135], 0, s[0:1]
	s_cmp_eq_u32 s55, 6
	s_waitcnt vmcnt(0)
	v_pk_mul_f32 v[16:17], v[16:17], v[66:67] op_sel_hi:[1,0]
	v_pk_mul_f32 v[8:9], v[8:9], v[66:67] op_sel_hi:[1,0]
	v_pk_mul_f32 v[4:5], v[4:5], v[66:67] op_sel_hi:[1,0]
	v_pk_mul_f32 v[2:3], v[2:3], v[66:67] op_sel_hi:[1,0]
	v_pk_mul_f32 v[32:33], v[32:33], v[66:67] op_sel_hi:[1,0]
	v_pk_mul_f32 v[64:65], v[64:65], v[66:67] op_sel_hi:[1,0]
	v_pk_mul_f32 v[62:63], v[62:63], v[66:67] op_sel_hi:[1,0]
	v_pk_mul_f32 v[14:15], v[14:15], v[66:67] op_sel_hi:[1,0]
	v_pk_mul_f32 v[12:13], v[12:13], v[66:67] op_sel_hi:[1,0]
	v_pk_mul_f32 v[10:11], v[10:11], v[66:67] op_sel_hi:[1,0]
	v_pk_mul_f32 v[6:7], v[6:7], v[66:67] op_sel_hi:[1,0]
	v_pk_mul_f32 v[30:31], v[30:31], v[66:67] op_sel_hi:[1,0]
	v_pk_mul_f32 v[28:29], v[28:29], v[66:67] op_sel_hi:[1,0]
	v_pk_mul_f32 v[26:27], v[26:27], v[66:67] op_sel_hi:[1,0]
	v_pk_mul_f32 v[24:25], v[24:25], v[66:67] op_sel_hi:[1,0]
	v_pk_mul_f32 v[22:23], v[22:23], v[66:67] op_sel_hi:[1,0]
	v_pk_mul_f32 v[20:21], v[20:21], v[66:67] op_sel_hi:[1,0]
	v_pk_mul_f32 v[18:19], v[18:19], v[66:67] op_sel_hi:[1,0]
	v_pk_mul_f32 v[48:49], v[48:49], v[66:67] op_sel_hi:[1,0]
	v_pk_mul_f32 v[46:47], v[46:47], v[66:67] op_sel_hi:[1,0]
	v_pk_mul_f32 v[44:45], v[44:45], v[66:67] op_sel_hi:[1,0]
	v_pk_mul_f32 v[42:43], v[42:43], v[66:67] op_sel_hi:[1,0]
	v_pk_mul_f32 v[40:41], v[40:41], v[66:67] op_sel_hi:[1,0]
	v_pk_mul_f32 v[38:39], v[38:39], v[66:67] op_sel_hi:[1,0]
	v_pk_mul_f32 v[36:37], v[36:37], v[66:67] op_sel_hi:[1,0]
	v_pk_mul_f32 v[34:35], v[34:35], v[66:67] op_sel_hi:[1,0]
	v_pk_mul_f32 v[60:61], v[60:61], v[66:67] op_sel_hi:[1,0]
	v_pk_mul_f32 v[58:59], v[58:59], v[66:67] op_sel_hi:[1,0]
	v_pk_mul_f32 v[56:57], v[56:57], v[66:67] op_sel_hi:[1,0]
	v_pk_mul_f32 v[54:55], v[54:55], v[66:67] op_sel_hi:[1,0]
	v_pk_mul_f32 v[52:53], v[52:53], v[66:67] op_sel_hi:[1,0]
	v_pk_mul_f32 v[50:51], v[50:51], v[66:67] op_sel_hi:[1,0]
	v_cvt_pk_bf16_f32 v2, v2, v3
	v_cvt_pk_bf16_f32 v3, v4, v5
	v_cvt_pk_bf16_f32 v5, v8, v9
	v_cvt_pk_bf16_f32 v9, v16, v17
	v_cvt_pk_bf16_f32 v17, v32, v33
	v_cvt_pk_bf16_f32 v32, v62, v63
	v_cvt_pk_bf16_f32 v33, v64, v65
	v_cvt_pk_bf16_f32 v4, v6, v7
	v_cvt_pk_bf16_f32 v6, v10, v11
	v_cvt_pk_bf16_f32 v7, v12, v13
	v_cvt_pk_bf16_f32 v8, v14, v15
	v_cvt_pk_bf16_f32 v10, v18, v19
	v_cvt_pk_bf16_f32 v11, v20, v21
	v_cvt_pk_bf16_f32 v12, v22, v23
	v_cvt_pk_bf16_f32 v13, v24, v25
	v_cvt_pk_bf16_f32 v14, v26, v27
	v_cvt_pk_bf16_f32 v15, v28, v29
	v_cvt_pk_bf16_f32 v16, v30, v31
	v_cvt_pk_bf16_f32 v18, v34, v35
	v_cvt_pk_bf16_f32 v19, v36, v37
	v_cvt_pk_bf16_f32 v20, v38, v39
	v_cvt_pk_bf16_f32 v21, v40, v41
	v_cvt_pk_bf16_f32 v22, v42, v43
	v_cvt_pk_bf16_f32 v23, v44, v45
	v_cvt_pk_bf16_f32 v24, v46, v47
	v_cvt_pk_bf16_f32 v25, v48, v49
	v_cvt_pk_bf16_f32 v26, v50, v51
	v_cvt_pk_bf16_f32 v27, v52, v53
	v_cvt_pk_bf16_f32 v28, v54, v55
	v_cvt_pk_bf16_f32 v29, v56, v57
	v_cvt_pk_bf16_f32 v30, v58, v59
	v_cvt_pk_bf16_f32 v31, v60, v61
	v_mbcnt_lo_u32_b32 v36, -1, 0
	v_mbcnt_hi_u32_b32 v36, -1, v36
	v_and_b32_e32 v36, 32, v36
	v_lshrrev_b32_e32 v36, 2, v36
	v_mov_b32_e32 v37, 0
	v_lshl_add_u64 v[34:35], v[68:69], 0, v[36:37]
	v_permlane32_swap_b32_e32 v2, v4
	v_permlane32_swap_b32_e32 v3, v5
	v_permlane32_swap_b32_e32 v6, v8
	v_permlane32_swap_b32_e32 v7, v9
	v_permlane32_swap_b32_e32 v10, v12
	v_permlane32_swap_b32_e32 v11, v13
	v_permlane32_swap_b32_e32 v14, v16
	v_permlane32_swap_b32_e32 v15, v17
	v_permlane32_swap_b32_e32 v18, v20
	v_permlane32_swap_b32_e32 v19, v21
	v_permlane32_swap_b32_e32 v22, v24
	v_permlane32_swap_b32_e32 v23, v25
	v_permlane32_swap_b32_e32 v26, v28
	v_permlane32_swap_b32_e32 v27, v29
	v_permlane32_swap_b32_e32 v30, v32
	v_permlane32_swap_b32_e32 v31, v33
	global_store_dwordx4 v[34:35], v[2:5], off
	global_store_dwordx4 v[34:35], v[6:9], off offset:32
	global_store_dwordx4 v[34:35], v[10:13], off offset:64
	global_store_dwordx4 v[34:35], v[14:17], off offset:96
	global_store_dwordx4 v[34:35], v[18:21], off offset:128
	global_store_dwordx4 v[34:35], v[22:25], off offset:160
	global_store_dwordx4 v[34:35], v[26:29], off offset:192
	global_store_dwordx4 v[34:35], v[30:33], off offset:224
	s_cbranch_scc1 .LBB0_3663
